# attention epilogue: c_norm loads hoisted out of the store chain; xcd barrier init: 16 counter loads issued together
# speedup vs baseline: 1.0303x; 1.0013x over previous
; __device__ __forceinline__ void attn_item(const int tid, char* smem, const Params& p, int l, int item) {
;     ...
;     bf16x8 pf[2][2];
; #pragma unroll
;     for (int h = 0; h < 2; ++h) {
;       float mx = -INFINITY;
; #pragma unroll
;       for (int kb = 0; kb < 4; ++kb)
; #pragma unroll
;         for (int r = 0; r < 4; ++r) mx = fmaxf(mx, S[h][kb][r]);
;       mx = fmaxf(mx, __shfl_xor(mx, 16));
;       mx = fmaxf(mx, __shfl_xor(mx, 32));
;       const float mold = mrun[h];
;       const float mnew = fmaxf(mold, mx);
;       mrun[h] = mnew;
;       float ps = 0.f;
;       float pv[4][4];
; #pragma unroll
;       for (int kb = 0; kb < 4; ++kb)
; #pragma unroll
;         for (int r = 0; r < 4; ++r) {
;           pv[kb][r] = __builtin_amdgcn_exp2f(S[h][kb][r] - mnew);
;           ps += pv[kb][r];
;         }
;       if (__builtin_amdgcn_ballot_w64(mnew > mold) != 0ull) {
;         const float alpha = __builtin_amdgcn_exp2f(mold - mnew);
;         lrun[h] *= alpha;
; #pragma unroll
;         for (int vb = 0; vb < 8; ++vb) O[h][vb] *= alpha;
;       }
;       lrun[h] += ps;
; #pragma unroll
;       for (int s = 0; s < 2; ++s) {
;         u32x4 cv;
;         cv.x = pack2(pv[2 * s][0], pv[2 * s][1]);
;         cv.y = pack2(pv[2 * s][2], pv[2 * s][3]);
;         cv.z = pack2(pv[2 * s + 1][0], pv[2 * s + 1][1]);
;         cv.w = pack2(pv[2 * s + 1][2], pv[2 * s + 1][3]);
;         pf[h][s] = __builtin_bit_cast(bf16x8, cv);
;       }
;     }
; #pragma unroll
;     for (int vb = 0; vb < 8; ++vb)
; #pragma unroll
;       for (int s = 0; s < 2; ++s) {
;         const bf16x8 vf = *reinterpret_cast<const bf16x8*>(Vs + (vb * 16 + fr) * 288 + (32 * s + 8 * fq) * 2);
;         O[0][vb] = __builtin_amdgcn_mfma_f32_16x16x32_bf16(vf, pf[0][s], O[0][vb], 0, 0, 0);
;         O[1][vb] = __builtin_amdgcn_mfma_f32_16x16x32_bf16(vf, pf[1][s], O[1][vb], 0, 0, 0);
;       }
.LBB0_104:
	v_sub_f32_e32 v128, v128, v17
	v_exp_f32_e32 v128, v128
	v_sub_f32_e32 v129, v129, v17
	v_exp_f32_e32 v129, v129
	v_sub_f32_e32 v130, v130, v17
	v_exp_f32_e32 v130, v130
	v_sub_f32_e32 v131, v131, v17
	v_exp_f32_e32 v131, v131
	v_sub_f32_e32 v124, v124, v17
	v_add_f32_e32 v148, 0, v128
	v_exp_f32_e32 v124, v124
	v_sub_f32_e32 v125, v125, v17
	v_add_f32_e32 v148, v129, v148
	v_exp_f32_e32 v125, v125
	v_sub_f32_e32 v126, v126, v17
	v_add_f32_e32 v148, v130, v148
	v_exp_f32_e32 v126, v126
	v_sub_f32_e32 v127, v127, v17
	v_add_f32_e32 v148, v131, v148
	v_exp_f32_e32 v127, v127
	v_sub_f32_e32 v104, v104, v17
	v_sub_f32_e32 v120, v120, v19
	v_add_f32_e32 v148, v124, v148
	v_exp_f32_e32 v149, v104
	v_exp_f32_e32 v120, v120
	v_sub_f32_e32 v121, v121, v19
	v_add_f32_e32 v148, v125, v148
	v_exp_f32_e32 v121, v121
	v_sub_f32_e32 v122, v122, v19
	v_add_f32_e32 v148, v126, v148
	v_exp_f32_e32 v122, v122
	v_sub_f32_e32 v123, v123, v19
	v_add_f32_e32 v148, v127, v148
	v_sub_f32_e32 v105, v105, v17
	v_exp_f32_e32 v123, v123
	v_sub_f32_e32 v116, v116, v19
	v_add_f32_e32 v104, v149, v148
	v_exp_f32_e32 v148, v105
	v_sub_f32_e32 v105, v106, v17
	v_cvt_pk_bf16_f32 v106, v124, v125
	v_add_f32_e32 v124, 0, v120
	v_exp_f32_e32 v116, v116
	v_sub_f32_e32 v117, v117, v19
	v_add_f32_e32 v124, v121, v124
	v_exp_f32_e32 v117, v117
	v_sub_f32_e32 v118, v118, v19
	v_add_f32_e32 v124, v122, v124
	v_exp_f32_e32 v118, v118
	v_sub_f32_e32 v119, v119, v19
	v_add_f32_e32 v124, v123, v124
	v_exp_f32_e32 v119, v119
	v_sub_f32_e32 v112, v112, v19
	v_add_f32_e32 v124, v116, v124
	v_exp_f32_e32 v125, v112
	v_add_f32_e32 v124, v117, v124
	v_add_f32_e32 v124, v118, v124
	v_exp_f32_e32 v150, v105
	v_sub_f32_e32 v105, v107, v17
	v_add_f32_e32 v124, v119, v124
	v_sub_f32_e32 v113, v113, v19
	v_exp_f32_e32 v151, v105
	v_sub_f32_e32 v100, v100, v17
	v_add_f32_e32 v112, v125, v124
	v_exp_f32_e32 v124, v113
	v_sub_f32_e32 v113, v114, v19
	v_exp_f32_e32 v216, v100
	v_cvt_pk_bf16_f32 v107, v126, v127
	v_exp_f32_e32 v126, v113
	v_sub_f32_e32 v113, v115, v19
	v_cvt_pk_bf16_f32 v114, v116, v117
	v_cvt_pk_bf16_f32 v115, v118, v119
	ds_read_b128 v[116:119], v16 offset:18432
	v_add_f32_e32 v104, v148, v104
	v_add_f32_e32 v104, v150, v104
	v_add_f32_e32 v104, v151, v104
	v_exp_f32_e32 v127, v113
	v_sub_f32_e32 v108, v108, v19
	v_add_f32_e32 v100, v216, v104
	v_cvt_pk_bf16_f32 v104, v128, v129
	v_exp_f32_e32 v128, v108
	v_add_f32_e32 v112, v124, v112
	v_add_f32_e32 v112, v126, v112
	v_add_f32_e32 v112, v127, v112
	v_cvt_pk_bf16_f32 v105, v130, v131
	v_add_f32_e32 v108, v128, v112
	v_cvt_pk_bf16_f32 v112, v120, v121
	v_cvt_pk_bf16_f32 v113, v122, v123
	v_sub_f32_e32 v101, v101, v17
	v_sub_f32_e32 v109, v109, v19
	s_waitcnt lgkmcnt(0)
	v_mfma_f32_16x16x32_bf16 v[84:87], v[116:119], v[104:107], v[84:87]
	v_exp_f32_e32 v217, v101
	v_sub_f32_e32 v101, v102, v17
	v_exp_f32_e32 v129, v109
	v_mfma_f32_16x16x32_bf16 v[88:91], v[116:119], v[112:115], v[88:91]
	ds_read_b128 v[116:119], v16 offset:18496
	ds_read_b128 v[120:123], v16 offset:23040
	v_sub_f32_e32 v109, v110, v19
	v_exp_f32_e32 v218, v101
	v_sub_f32_e32 v101, v103, v17
	v_exp_f32_e32 v130, v109
	v_sub_f32_e32 v109, v111, v19
	v_exp_f32_e32 v103, v101
	v_exp_f32_e32 v111, v109
	v_add_f32_e32 v100, v217, v100
	v_add_f32_e32 v108, v129, v108
	v_add_f32_e32 v100, v218, v100
	v_add_f32_e32 v108, v130, v108
	v_add_f32_e32 v100, v103, v100
	v_add_f32_e32 v108, v111, v108
	v_add_f32_e32 v155, v100, v155
	v_cvt_pk_bf16_f32 v100, v149, v148
	v_cvt_pk_bf16_f32 v101, v150, v151
	v_cvt_pk_bf16_f32 v102, v216, v217
	v_cvt_pk_bf16_f32 v103, v218, v103
	v_add_f32_e32 v215, v108, v215
	v_cvt_pk_bf16_f32 v108, v125, v124
	v_cvt_pk_bf16_f32 v109, v126, v127
	v_cvt_pk_bf16_f32 v110, v128, v129
	v_cvt_pk_bf16_f32 v111, v130, v111
	ds_read_b128 v[124:127], v16 offset:23104
	ds_read_b128 v[128:131], v16 offset:27648
	s_waitcnt lgkmcnt(3)
	v_mfma_f32_16x16x32_bf16 v[84:87], v[116:119], v[100:103], v[84:87]
	v_mfma_f32_16x16x32_bf16 v[88:91], v[116:119], v[108:111], v[88:91]
	ds_read_b128 v[116:119], v16 offset:27712
	v_lshl_add_u64 v[164:165], v[164:165], 0, s[38:39]
	v_lshl_add_u64 v[166:167], v[166:167], 0, s[38:39]
	v_lshl_add_u64 v[168:169], v[168:169], 0, s[4:5]
	v_lshl_add_u64 v[170:171], v[170:171], 0, s[4:5]
	s_cmp_lg_u32 s11, s0
	s_waitcnt lgkmcnt(3)
	v_mfma_f32_16x16x32_bf16 v[72:75], v[120:123], v[104:107], v[72:75]
	v_mfma_f32_16x16x32_bf16 v[80:83], v[120:123], v[112:115], v[80:83]
	ds_read_b128 v[120:123], v16 offset:32256
	s_waitcnt lgkmcnt(3)
	v_mfma_f32_16x16x32_bf16 v[72:75], v[124:127], v[100:103], v[72:75]
	v_mfma_f32_16x16x32_bf16 v[80:83], v[124:127], v[108:111], v[80:83]
	ds_read_b128 v[124:127], v16 offset:32320
	s_waitcnt lgkmcnt(3)
	v_mfma_f32_16x16x32_bf16 v[60:63], v[128:131], v[104:107], v[60:63]
	v_mfma_f32_16x16x32_bf16 v[76:79], v[128:131], v[112:115], v[76:79]
	ds_read_b128 v[128:131], v16 offset:36864
	s_waitcnt lgkmcnt(3)
	v_mfma_f32_16x16x32_bf16 v[60:63], v[116:119], v[100:103], v[60:63]
	v_mfma_f32_16x16x32_bf16 v[76:79], v[116:119], v[108:111], v[76:79]
	ds_read_b128 v[116:119], v16 offset:36928
	s_waitcnt lgkmcnt(3)
	v_mfma_f32_16x16x32_bf16 v[48:51], v[120:123], v[104:107], v[48:51]
	v_mfma_f32_16x16x32_bf16 v[64:67], v[120:123], v[112:115], v[64:67]
	ds_read_b128 v[120:123], v16 offset:41472
	s_waitcnt lgkmcnt(3)
	v_mfma_f32_16x16x32_bf16 v[48:51], v[124:127], v[100:103], v[48:51]
	v_mfma_f32_16x16x32_bf16 v[64:67], v[124:127], v[108:111], v[64:67]
	ds_read_b128 v[124:127], v16 offset:41536
	s_waitcnt lgkmcnt(3)
	v_mfma_f32_16x16x32_bf16 v[36:39], v[128:131], v[104:107], v[36:39]
	v_mfma_f32_16x16x32_bf16 v[44:47], v[128:131], v[112:115], v[44:47]
	ds_read_b128 v[128:131], v16 offset:46080
	s_waitcnt lgkmcnt(3)
	v_mfma_f32_16x16x32_bf16 v[36:39], v[116:119], v[100:103], v[36:39]
	v_mfma_f32_16x16x32_bf16 v[44:47], v[116:119], v[108:111], v[44:47]
	ds_read_b128 v[116:119], v16 offset:46144
	s_waitcnt lgkmcnt(3)
	v_mfma_f32_16x16x32_bf16 v[56:59], v[120:123], v[104:107], v[56:59]
	v_mfma_f32_16x16x32_bf16 v[68:71], v[120:123], v[112:115], v[68:71]
	ds_read_b128 v[120:123], v16 offset:50688
	s_waitcnt lgkmcnt(3)
	v_mfma_f32_16x16x32_bf16 v[56:59], v[124:127], v[100:103], v[56:59]
	v_mfma_f32_16x16x32_bf16 v[68:71], v[124:127], v[108:111], v[68:71]
	ds_read_b128 v[124:127], v16 offset:50752
	s_waitcnt lgkmcnt(3)
	v_mfma_f32_16x16x32_bf16 v[40:43], v[128:131], v[104:107], v[40:43]
	v_mfma_f32_16x16x32_bf16 v[52:55], v[128:131], v[112:115], v[52:55]
	s_waitcnt lgkmcnt(0)
	s_barrier
; __device__ __forceinline__ void attn_item(const int tid, char* smem, const Params& p, int l, int item) {
;     ...
; #pragma unroll
;     for (int vb = 0; vb < 8; ++vb)
; #pragma unroll
;       for (int s = 0; s < 2; ++s) {
;         const bf16x8 vf = *reinterpret_cast<const bf16x8*>(Vs + (vb * 16 + fr) * 288 + (32 * s + 8 * fq) * 2);
;         O[0][vb] = __builtin_amdgcn_mfma_f32_16x16x32_bf16(vf, pf[0][s], O[0][vb], 0, 0, 0);
;         O[1][vb] = __builtin_amdgcn_mfma_f32_16x16x32_bf16(vf, pf[1][s], O[1][vb], 0, 0, 0);
;       }
;     __syncthreads();
;   }
;   float linv[2];
; #pragma unroll
;   for (int h = 0; h < 2; ++h) {
;     float lt = lrun[h];
;     lt += __shfl_xor(lt, 16);
;     lt += __shfl_xor(lt, 32);
;     linv[h] = 1.f / lt;
;   }
;   float ss = 0.f;
;   float ov[8][4];
; #pragma unroll
;   for (int vb = 0; vb < 8; ++vb)
; #pragma unroll
;     for (int r = 0; r < 4; ++r) {
;       float o = O[0][vb][r] * linv[0] - lam * (O[1][vb][r] * linv[1]);
;       ov[vb][r] = o;
;       ss += o * o;
;     }
;   ss += __shfl_xor(ss, 16);
;   ss += __shfl_xor(ss, 32);
;   float rn = rsqrtf(ss * (1.f / 128.f) + EPS) * (1.f - lam_init);
; #pragma unroll
;   for (int vb = 0; vb < 8; ++vb) {
;     int v0 = vb * 16 + 4 * fq;
;     float4 g = *reinterpret_cast<const float4*>(p.c_norm + l * 128 + v0);
;     uint2 o;
;     o.x = pack2(ov[vb][0] * rn * g.x, ov[vb][1] * rn * g.y);
;     o.y = pack2(ov[vb][2] * rn * g.z, ov[vb][3] * rn * g.w);
;     *reinterpret_cast<uint2*>(mix + (size_t)qrow * DM + 1024 + hd * 128 + v0) = o;
	v_mfma_f32_16x16x32_bf16 v[40:43], v[116:119], v[100:103], v[40:43]
	v_mfma_f32_16x16x32_bf16 v[52:55], v[116:119], v[108:111], v[52:55]
	v_mfma_f32_16x16x32_bf16 v[92:95], v[120:123], v[104:107], v[92:95]
	v_mfma_f32_16x16x32_bf16 v[96:99], v[120:123], v[112:115], v[96:99]
	v_mfma_f32_16x16x32_bf16 v[92:95], v[124:127], v[100:103], v[92:95]
	v_mfma_f32_16x16x32_bf16 v[96:99], v[124:127], v[108:111], v[96:99]
	s_cbranch_scc1 .LBB0_96
	v_add_f32_e32 v0, v161, v212
	ds_bpermute_b32 v1, v205, v0
	v_add_f32_e32 v2, v213, v214
	s_mov_b32 s0, 0x3fb8aa3b
	ds_bpermute_b32 v3, v205, v2
	ds_bpermute_b32 v6, v172, v155
	s_waitcnt lgkmcnt(2)
	v_add_f32_e32 v0, v0, v1
	v_mul_f32_e32 v1, 0x3fb8aa3b, v0
	v_fma_f32 v4, v0, s0, -v1
	v_rndne_f32_e32 v5, v1
	v_fmac_f32_e32 v4, 0x32a5705f, v0
	v_sub_f32_e32 v1, v1, v5
	v_add_f32_e32 v1, v1, v4
	v_cvt_i32_f32_e32 v4, v5
	v_exp_f32_e32 v1, v1
	s_waitcnt lgkmcnt(1)
	v_add_f32_e32 v2, v2, v3
	v_mul_f32_e32 v3, 0x3fb8aa3b, v2
	v_rndne_f32_e32 v5, v3
	v_ldexp_f32 v1, v1, v4
	v_fma_f32 v4, v2, s0, -v3
	v_fmac_f32_e32 v4, 0x32a5705f, v2
	v_sub_f32_e32 v3, v3, v5
	v_add_f32_e32 v3, v3, v4
	v_exp_f32_e32 v3, v3
	v_cvt_i32_f32_e32 v4, v5
	s_mov_b32 s1, 0xc2ce8ed0
	v_cmp_ngt_f32_e32 vcc, s1, v0
	s_waitcnt lgkmcnt(0)
	v_add_f32_e32 v5, v155, v6
	s_mov_b32 s2, 0x42b17218
	v_cndmask_b32_e32 v1, 0, v1, vcc
	ds_bpermute_b32 v6, v153, v5
	v_cmp_nlt_f32_e32 vcc, s2, v0
	s_lshl_b32 s92, s10, 1
	v_mov_b32_e32 v161, v18
	v_cndmask_b32_e32 v0, v188, v1, vcc
	v_ldexp_f32 v1, v3, v4
	v_cmp_ngt_f32_e32 vcc, s1, v2
	s_waitcnt lgkmcnt(0)
	v_add_f32_e32 v3, v5, v6
	v_div_scale_f32 v4, s[0:1], v3, v3, 1.0
	v_cndmask_b32_e32 v1, 0, v1, vcc
	v_cmp_nlt_f32_e32 vcc, s2, v2
	v_rcp_f32_e32 v5, v4
	s_movk_i32 s49, 0xff
	v_cndmask_b32_e32 v1, v188, v1, vcc
	v_sub_f32_e32 v0, v0, v1
	ds_bpermute_b32 v1, v172, v215
	v_fma_f32 v2, -v4, v5, 1.0
	v_fmac_f32_e32 v5, v2, v5
	v_div_scale_f32 v2, vcc, 1.0, v3, 1.0
	s_waitcnt lgkmcnt(0)
	v_add_f32_e32 v1, v215, v1
	ds_bpermute_b32 v6, v153, v1
	v_mul_f32_e32 v7, v2, v5
	v_fma_f32 v8, -v4, v7, v2
	v_fmac_f32_e32 v7, v8, v5
	v_fma_f32 v2, -v4, v7, v2
	s_waitcnt lgkmcnt(0)
	v_add_f32_e32 v1, v1, v6
	v_div_scale_f32 v4, s[0:1], v1, v1, 1.0
	v_rcp_f32_e32 v6, v4
	v_div_fmas_f32 v2, v2, v5, v7
	v_div_fixup_f32 v8, v2, v3, 1.0
	v_add_f32_e32 v12, v209, v0
	v_fma_f32 v2, -v4, v6, 1.0
	v_fmac_f32_e32 v6, v2, v6
	v_div_scale_f32 v2, vcc, 1.0, v1, 1.0
	v_mul_f32_e32 v3, v2, v6
	v_fma_f32 v5, -v4, v3, v2
	v_fmac_f32_e32 v3, v5, v6
	v_fma_f32 v2, -v4, v3, v2
	v_div_fmas_f32 v2, v2, v6, v3
	v_div_fixup_f32 v10, v2, v1, 1.0
	v_pk_mul_f32 v[4:5], v[90:91], v[10:11] op_sel_hi:[1,0]
	s_waitcnt vmcnt(1)
	v_pk_mul_f32 v[24:25], v[88:89], v[10:11] op_sel_hi:[1,0]
	v_pk_mul_f32 v[4:5], v[12:13], v[4:5] op_sel_hi:[0,1]
	s_waitcnt vmcnt(0)
	v_pk_fma_f32 v[20:21], v[86:87], v[8:9], v[4:5] op_sel_hi:[1,0,1] neg_lo:[0,0,1] neg_hi:[0,0,1]
	global_load_dwordx4 v[4:7], v[138:139], off
	global_load_dwordx4 v[100:103], v[138:139], off offset:64
	global_load_dwordx4 v[104:107], v[138:139], off offset:128
	global_load_dwordx4 v[108:111], v[138:139], off offset:192
	global_load_dwordx4 v[112:115], v[138:139], off offset:256
	global_load_dwordx4 v[116:119], v[138:139], off offset:320
	global_load_dwordx4 v[120:123], v[138:139], off offset:384
	global_load_dwordx4 v[124:127], v[138:139], off offset:448
	v_pk_mul_f32 v[24:25], v[12:13], v[24:25] op_sel_hi:[0,1]
	v_pk_mul_f32 v[28:29], v[82:83], v[10:11] op_sel_hi:[1,0]
	v_pk_mul_f32 v[32:33], v[80:81], v[10:11] op_sel_hi:[1,0]
	v_pk_fma_f32 v[24:25], v[84:85], v[8:9], v[24:25] op_sel_hi:[1,0,1] neg_lo:[0,0,1] neg_hi:[0,0,1]
	v_pk_mul_f32 v[28:29], v[12:13], v[28:29] op_sel_hi:[0,1]
	v_pk_mul_f32 v[32:33], v[12:13], v[32:33] op_sel_hi:[0,1]
	v_pk_mul_f32 v[0:1], v[96:97], v[10:11] op_sel_hi:[1,0]
	v_pk_mul_f32 v[2:3], v[98:99], v[10:11] op_sel_hi:[1,0]
	v_pk_mul_f32 v[26:27], v[24:25], v[24:25]
	v_pk_fma_f32 v[28:29], v[74:75], v[8:9], v[28:29] op_sel_hi:[1,0,1] neg_lo:[0,0,1] neg_hi:[0,0,1]
	v_pk_fma_f32 v[32:33], v[72:73], v[8:9], v[32:33] op_sel_hi:[1,0,1] neg_lo:[0,0,1] neg_hi:[0,0,1]
	v_pk_mul_f32 v[72:73], v[78:79], v[10:11] op_sel_hi:[1,0]
	v_pk_mul_f32 v[74:75], v[76:77], v[10:11] op_sel_hi:[1,0]
	v_pk_mul_f32 v[66:67], v[66:67], v[10:11] op_sel_hi:[1,0]
	v_pk_mul_f32 v[64:65], v[64:65], v[10:11] op_sel_hi:[1,0]
	v_pk_mul_f32 v[46:47], v[46:47], v[10:11] op_sel_hi:[1,0]
	v_pk_mul_f32 v[44:45], v[44:45], v[10:11] op_sel_hi:[1,0]
	v_pk_mul_f32 v[70:71], v[70:71], v[10:11] op_sel_hi:[1,0]
	v_pk_mul_f32 v[68:69], v[68:69], v[10:11] op_sel_hi:[1,0]
	v_pk_mul_f32 v[54:55], v[54:55], v[10:11] op_sel_hi:[1,0]
	v_pk_mul_f32 v[10:11], v[52:53], v[10:11] op_sel_hi:[1,0]
	v_pk_mul_f32 v[0:1], v[12:13], v[0:1] op_sel_hi:[0,1]
	v_pk_mul_f32 v[2:3], v[12:13], v[2:3] op_sel_hi:[0,1]
	v_pk_mul_f32 v[22:23], v[20:21], v[20:21]
	v_pk_mul_f32 v[72:73], v[12:13], v[72:73] op_sel_hi:[0,1]
	v_pk_mul_f32 v[74:75], v[12:13], v[74:75] op_sel_hi:[0,1]
	v_pk_mul_f32 v[66:67], v[12:13], v[66:67] op_sel_hi:[0,1]
	v_pk_mul_f32 v[64:65], v[12:13], v[64:65] op_sel_hi:[0,1]
	v_pk_mul_f32 v[46:47], v[12:13], v[46:47] op_sel_hi:[0,1]
	v_pk_mul_f32 v[44:45], v[12:13], v[44:45] op_sel_hi:[0,1]
	v_pk_mul_f32 v[70:71], v[12:13], v[70:71] op_sel_hi:[0,1]
	v_pk_mul_f32 v[68:69], v[12:13], v[68:69] op_sel_hi:[0,1]
	v_pk_mul_f32 v[54:55], v[12:13], v[54:55] op_sel_hi:[0,1]
	v_pk_mul_f32 v[10:11], v[12:13], v[10:11] op_sel_hi:[0,1]
	v_add_f32_e32 v12, v26, v27
	v_add_f32_e32 v12, v22, v12
	v_pk_mul_f32 v[34:35], v[32:33], v[32:33]
	v_add_f32_e32 v12, v23, v12
	v_add_f32_e32 v12, v34, v12
	v_pk_mul_f32 v[30:31], v[28:29], v[28:29]
; __device__ __forceinline__ void attn_item(const int tid, char* smem, const Params& p, int l, int item) {
;     ...
;   float ss = 0.f;
;   float ov[8][4];
; #pragma unroll
;   for (int vb = 0; vb < 8; ++vb)
; #pragma unroll
;     for (int r = 0; r < 4; ++r) {
;       float o = O[0][vb][r] * linv[0] - lam * (O[1][vb][r] * linv[1]);
;       ov[vb][r] = o;
;       ss += o * o;
;     }
;   ss += __shfl_xor(ss, 16);
;   ss += __shfl_xor(ss, 32);
;   float rn = rsqrtf(ss * (1.f / 128.f) + EPS) * (1.f - lam_init);
; #pragma unroll
;   for (int vb = 0; vb < 8; ++vb) {
;     int v0 = vb * 16 + 4 * fq;
;     float4 g = *reinterpret_cast<const float4*>(p.c_norm + l * 128 + v0);
;     uint2 o;
;     o.x = pack2(ov[vb][0] * rn * g.x, ov[vb][1] * rn * g.y);
;     o.y = pack2(ov[vb][2] * rn * g.z, ov[vb][3] * rn * g.w);
;     *reinterpret_cast<uint2*>(mix + (size_t)qrow * DM + 1024 + hd * 128 + v0) = o;
;   }
	v_add_f32_e32 v12, v35, v12
	v_pk_fma_f32 v[60:61], v[60:61], v[8:9], v[74:75] op_sel_hi:[1,0,1] neg_lo:[0,0,1] neg_hi:[0,0,1]
	v_add_f32_e32 v12, v30, v12
	v_pk_mul_f32 v[74:75], v[60:61], v[60:61]
	v_add_f32_e32 v12, v31, v12
	v_pk_fma_f32 v[62:63], v[62:63], v[8:9], v[72:73] op_sel_hi:[1,0,1] neg_lo:[0,0,1] neg_hi:[0,0,1]
	v_add_f32_e32 v12, v74, v12
	v_pk_mul_f32 v[72:73], v[62:63], v[62:63]
	v_add_f32_e32 v12, v75, v12
	v_pk_fma_f32 v[48:49], v[48:49], v[8:9], v[64:65] op_sel_hi:[1,0,1] neg_lo:[0,0,1] neg_hi:[0,0,1]
	v_add_f32_e32 v12, v72, v12
	v_pk_mul_f32 v[64:65], v[48:49], v[48:49]
	v_add_f32_e32 v12, v73, v12
	v_pk_fma_f32 v[50:51], v[50:51], v[8:9], v[66:67] op_sel_hi:[1,0,1] neg_lo:[0,0,1] neg_hi:[0,0,1]
	v_add_f32_e32 v12, v64, v12
	v_pk_mul_f32 v[66:67], v[50:51], v[50:51]
	v_add_f32_e32 v12, v65, v12
	v_pk_fma_f32 v[36:37], v[36:37], v[8:9], v[44:45] op_sel_hi:[1,0,1] neg_lo:[0,0,1] neg_hi:[0,0,1]
	v_add_f32_e32 v12, v66, v12
	v_pk_mul_f32 v[44:45], v[36:37], v[36:37]
	v_add_f32_e32 v12, v67, v12
	v_pk_fma_f32 v[38:39], v[38:39], v[8:9], v[46:47] op_sel_hi:[1,0,1] neg_lo:[0,0,1] neg_hi:[0,0,1]
	v_add_f32_e32 v12, v44, v12
	v_pk_mul_f32 v[46:47], v[38:39], v[38:39]
	v_add_f32_e32 v12, v45, v12
	v_pk_fma_f32 v[56:57], v[56:57], v[8:9], v[68:69] op_sel_hi:[1,0,1] neg_lo:[0,0,1] neg_hi:[0,0,1]
	v_add_f32_e32 v12, v46, v12
	v_pk_mul_f32 v[68:69], v[56:57], v[56:57]
	v_add_f32_e32 v12, v47, v12
	v_pk_fma_f32 v[58:59], v[58:59], v[8:9], v[70:71] op_sel_hi:[1,0,1] neg_lo:[0,0,1] neg_hi:[0,0,1]
	v_add_f32_e32 v12, v68, v12
	v_pk_mul_f32 v[70:71], v[58:59], v[58:59]
	v_add_f32_e32 v12, v69, v12
	v_pk_fma_f32 v[0:1], v[92:93], v[8:9], v[0:1] op_sel_hi:[1,0,1] neg_lo:[0,0,1] neg_hi:[0,0,1]
	v_pk_fma_f32 v[2:3], v[94:95], v[8:9], v[2:3] op_sel_hi:[1,0,1] neg_lo:[0,0,1] neg_hi:[0,0,1]
	v_pk_fma_f32 v[42:43], v[42:43], v[8:9], v[54:55] op_sel_hi:[1,0,1] neg_lo:[0,0,1] neg_hi:[0,0,1]
	v_pk_fma_f32 v[8:9], v[40:41], v[8:9], v[10:11] op_sel_hi:[1,0,1] neg_lo:[0,0,1] neg_hi:[0,0,1]
	v_add_f32_e32 v12, v70, v12
	v_pk_mul_f32 v[10:11], v[8:9], v[8:9]
	v_add_f32_e32 v12, v71, v12
	v_add_f32_e32 v10, v10, v12
	v_pk_mul_f32 v[54:55], v[42:43], v[42:43]
	v_add_f32_e32 v10, v11, v10
	v_add_f32_e32 v10, v54, v10
	v_pk_mul_f32 v[14:15], v[0:1], v[0:1]
	v_add_f32_e32 v10, v55, v10
	v_add_f32_e32 v10, v14, v10
	v_pk_mul_f32 v[16:17], v[2:3], v[2:3]
	v_add_f32_e32 v10, v15, v10
	v_add_f32_e32 v10, v16, v10
	v_add_f32_e32 v10, v17, v10
	ds_bpermute_b32 v11, v172, v10
	s_mov_b32 s0, 0x2d974000
	s_waitcnt lgkmcnt(0)
	v_add_f32_e32 v12, v10, v11
	ds_bpermute_b32 v13, v153, v12
	v_lshlrev_b64 v[10:11], 12, v[162:163]
	v_lshl_add_u64 v[10:11], s[90:91], 0, v[10:11]
	v_lshl_add_u64 v[10:11], v[10:11], 0, s[92:93]
	v_lshl_add_u64 v[10:11], v[10:11], 0, v[160:161]
	s_waitcnt lgkmcnt(0)
	v_add_f32_e32 v12, v12, v13
	v_fmamk_f32 v12, v12, 0x3c000000, v175
	v_mul_f32_e32 v13, 0x4b800000, v12
	v_cmp_gt_f32_e32 vcc, s96, v12
	s_mov_b32 s92, 0x7f800000
	s_nop 0
	v_cndmask_b32_e32 v12, v12, v13, vcc
	v_rsq_f32_e32 v12, v12
	s_nop 0
	v_mul_f32_e32 v13, 0x45800000, v12
	v_cndmask_b32_e32 v12, v12, v13, vcc
	v_mul_f32_e32 v12, v210, v12
	v_pk_mul_f32 v[14:15], v[24:25], v[12:13] op_sel_hi:[1,0]
	v_pk_mul_f32 v[16:17], v[62:63], v[12:13] op_sel_hi:[1,0]
	s_waitcnt vmcnt(0)
	v_pk_mul_f32 v[4:5], v[4:5], v[14:15]
	v_pk_mul_f32 v[14:15], v[20:21], v[12:13] op_sel_hi:[1,0]
	v_cvt_pk_bf16_f32 v4, v4, v5
	v_pk_mul_f32 v[6:7], v[6:7], v[14:15]
	v_pk_mul_f32 v[14:15], v[32:33], v[12:13] op_sel_hi:[1,0]
	v_cvt_pk_bf16_f32 v5, v6, v7
	v_add_co_u32_e32 v6, vcc, s0, v10
	s_mov_b64 s[0:1], 0x2d974800
	s_nop 0
	v_addc_co_u32_e32 v7, vcc, 0, v11, vcc
	global_store_dwordx2 v[6:7], v[4:5], off offset:2048
	v_lshl_add_u64 v[10:11], v[10:11], 0, s[0:1]
	v_pk_mul_f32 v[8:9], v[8:9], v[12:13] op_sel_hi:[1,0]
	v_readlane_b32 s0, v254, 54
	v_pk_mul_f32 v[0:1], v[0:1], v[12:13] op_sel_hi:[1,0]
	v_pk_mul_f32 v[2:3], v[2:3], v[12:13] op_sel_hi:[1,0]
	s_add_i32 s7, s7, s0
	s_cmp_ge_i32 s7, s6
	v_pk_mul_f32 v[4:5], v[100:101], v[14:15]
	v_pk_mul_f32 v[14:15], v[28:29], v[12:13] op_sel_hi:[1,0]
	v_cvt_pk_bf16_f32 v4, v4, v5
	v_pk_mul_f32 v[6:7], v[102:103], v[14:15]
	v_pk_mul_f32 v[14:15], v[60:61], v[12:13] op_sel_hi:[1,0]
	v_cvt_pk_bf16_f32 v5, v6, v7
	global_store_dwordx2 v[10:11], v[4:5], off offset:32
	v_pk_mul_f32 v[4:5], v[104:105], v[14:15]
	v_pk_mul_f32 v[6:7], v[106:107], v[16:17]
	v_cvt_pk_bf16_f32 v4, v4, v5
	v_cvt_pk_bf16_f32 v5, v6, v7
	global_store_dwordx2 v[10:11], v[4:5], off offset:64
	v_pk_mul_f32 v[14:15], v[48:49], v[12:13] op_sel_hi:[1,0]
	v_pk_mul_f32 v[16:17], v[50:51], v[12:13] op_sel_hi:[1,0]
	v_pk_mul_f32 v[4:5], v[108:109], v[14:15]
	v_pk_mul_f32 v[6:7], v[110:111], v[16:17]
	v_cvt_pk_bf16_f32 v4, v4, v5
	v_cvt_pk_bf16_f32 v5, v6, v7
	global_store_dwordx2 v[10:11], v[4:5], off offset:96
	v_pk_mul_f32 v[14:15], v[36:37], v[12:13] op_sel_hi:[1,0]
	v_pk_mul_f32 v[16:17], v[38:39], v[12:13] op_sel_hi:[1,0]
	v_pk_mul_f32 v[4:5], v[112:113], v[14:15]
	v_pk_mul_f32 v[6:7], v[114:115], v[16:17]
	v_cvt_pk_bf16_f32 v4, v4, v5
	v_cvt_pk_bf16_f32 v5, v6, v7
	global_store_dwordx2 v[10:11], v[4:5], off offset:128
	v_pk_mul_f32 v[14:15], v[56:57], v[12:13] op_sel_hi:[1,0]
	v_pk_mul_f32 v[16:17], v[58:59], v[12:13] op_sel_hi:[1,0]
	v_pk_mul_f32 v[4:5], v[116:117], v[14:15]
	v_pk_mul_f32 v[6:7], v[118:119], v[16:17]
	v_cvt_pk_bf16_f32 v4, v4, v5
	v_cvt_pk_bf16_f32 v5, v6, v7
	global_store_dwordx2 v[10:11], v[4:5], off offset:160
	v_pk_mul_f32 v[14:15], v[42:43], v[12:13] op_sel_hi:[1,0]
	v_pk_mul_f32 v[4:5], v[120:121], v[8:9]
	v_pk_mul_f32 v[6:7], v[122:123], v[14:15]
	v_cvt_pk_bf16_f32 v4, v4, v5
	v_cvt_pk_bf16_f32 v5, v6, v7
	global_store_dwordx2 v[10:11], v[4:5], off offset:192
	v_pk_mul_f32 v[0:1], v[124:125], v[0:1]
	v_pk_mul_f32 v[2:3], v[126:127], v[2:3]
	v_cvt_pk_bf16_f32 v0, v0, v1
	v_cvt_pk_bf16_f32 v1, v2, v3
	global_store_dwordx2 v[10:11], v[0:1], off offset:224
	s_barrier
	s_cbranch_scc0 .LBB0_91

; __device__ __forceinline__ unsigned xb_ld(unsigned* p)              { return __hip_atomic_load(p, __ATOMIC_RELAXED, __HIP_MEMORY_SCOPE_AGENT); }
; __device__ __forceinline__ void xcd_barrier_complete(unsigned* bar, unsigned x, unsigned& nloc, unsigned& nx) {
;   const unsigned G = gridDim.x * gridDim.y * gridDim.z;
;   unsigned sum, cnt, mine, sp = 0u;
;   for (;;) {
;     sum = 0u; cnt = 0u; mine = 0u;
; #pragma unroll
;     for (unsigned j = 0; j < 16; ++j) { const unsigned c = xb_ld(&bar[XB_XCNT(j)]); sum += c; cnt += (c > 0u) ? 1u : 0u; mine = (j == x) ? c : mine; }
;     if (sum == G) break;
;     __builtin_amdgcn_s_sleep(1);
;     if ((++sp & 255u) == 0u) { if (xb_ld(&bar[XB_TMO])) break; if (sp > XB_SPIN_CAP) { atomicAdd(&bar[XB_TMO], 1u); break; } }
;   }
.LBB0_966:
	v_readlane_b32 s2, v252, 57
	v_readlane_b32 s3, v252, 58
	s_mov_b64 s[6:7], -1
	s_waitcnt lgkmcnt(0)
	s_nop 4
	global_load_dword v0, v18, s[2:3] sc1
	v_readlane_b32 s2, v252, 59
	v_readlane_b32 s3, v252, 60
	s_nop 4
	global_load_dword v1, v18, s[2:3] sc1
	v_readlane_b32 s2, v252, 61
	v_readlane_b32 s3, v252, 62
	s_nop 4
	global_load_dword v2, v18, s[2:3] sc1
	v_readlane_b32 s2, v252, 63
	v_readlane_b32 s3, v253, 0
	s_nop 4
	global_load_dword v3, v18, s[2:3] sc1
	v_readlane_b32 s2, v253, 1
	v_readlane_b32 s3, v253, 2
	s_nop 4
	global_load_dword v4, v18, s[2:3] sc1
	v_readlane_b32 s2, v253, 3
	v_readlane_b32 s3, v253, 4
	s_nop 4
	global_load_dword v5, v18, s[2:3] sc1
	v_readlane_b32 s2, v253, 5
	v_readlane_b32 s3, v253, 6
	s_nop 4
	global_load_dword v6, v18, s[2:3] sc1
	v_readlane_b32 s2, v253, 7
	v_readlane_b32 s3, v253, 8
	s_nop 4
	global_load_dword v7, v18, s[2:3] sc1
	v_readlane_b32 s2, v253, 9
	v_readlane_b32 s3, v253, 10
	s_nop 4
	global_load_dword v8, v18, s[2:3] sc1
	v_readlane_b32 s2, v253, 11
	v_readlane_b32 s3, v253, 12
	s_nop 4
	global_load_dword v9, v18, s[2:3] sc1
	v_readlane_b32 s2, v253, 13
	v_readlane_b32 s3, v253, 14
	s_nop 4
	global_load_dword v10, v18, s[2:3] sc1
	v_readlane_b32 s2, v253, 15
	v_readlane_b32 s3, v253, 16
	s_nop 4
	global_load_dword v11, v18, s[2:3] sc1
	v_readlane_b32 s2, v253, 17
	v_readlane_b32 s3, v253, 18
	s_nop 4
	global_load_dword v12, v18, s[2:3] sc1
	v_readlane_b32 s2, v253, 19
	v_readlane_b32 s3, v253, 20
	s_nop 4
	global_load_dword v13, v18, s[2:3] sc1
	v_readlane_b32 s2, v253, 21
	v_readlane_b32 s3, v253, 22
	s_nop 4
	global_load_dword v14, v18, s[2:3] sc1
	v_readlane_b32 s2, v253, 23
	v_readlane_b32 s3, v253, 24
	s_nop 4
	global_load_dword v15, v18, s[2:3] sc1
	s_mov_b64 s[2:3], -1
	s_waitcnt vmcnt(0)
	v_add_u32_e32 v16, v1, v0
	v_add_u32_e32 v16, v16, v2
	v_add_u32_e32 v16, v16, v3
	v_add_u32_e32 v16, v16, v4
	v_add_u32_e32 v16, v16, v5
	v_add_u32_e32 v16, v16, v6
	v_add_u32_e32 v16, v16, v7
	v_add_u32_e32 v16, v16, v8
	v_add_u32_e32 v16, v16, v9
	v_add_u32_e32 v16, v16, v10
	v_add_u32_e32 v16, v16, v11
	v_add_u32_e32 v16, v16, v12
	v_add_u32_e32 v16, v16, v13
	v_add_u32_e32 v16, v16, v14
	v_add_u32_e32 v16, v16, v15
	v_cmp_eq_u32_e32 vcc, s97, v16
	s_cbranch_vccnz .LBB0_965
	s_and_b32 s2, s13, 0xff
	s_cmp_eq_u32 s2, 0
	s_mov_b64 s[2:3], -1
	s_mov_b64 s[10:11], -1
	s_sleep 1
	s_cbranch_scc1 .LBB0_970
	s_and_b64 vcc, exec, s[10:11]
	s_cbranch_vccz .LBB0_965
